# adaLN output loop: loop-invariant bias load hoisted out of the 5-iteration store loop (no per-iteration load round trip)
# baseline (speedup 1.0000x reference)
.LBB0_137:
	s_ashr_i32 s21, s20, 31
	v_or_b32_e32 v4, s20, v1
	v_mov_b32_e32 v2, s14
	v_mov_b32_e32 v3, s15
	v_ashrrev_i32_e32 v5, 31, v4
	s_lshl_b64 s[6:7], s[20:21], 2
	v_lshl_add_u64 v[2:3], v[4:5], 2, v[2:3]
	v_lshrrev_b32_e32 v8, 6, v158
	s_mov_b32 s8, 0xc000
	v_mov_b64_e32 v[4:5], s[6:7]
	v_mad_u64_u32 v[4:5], s[6:7], v8, s8, v[4:5]
	v_lshlrev_b32_e32 v8, 2, v1
	v_mov_b32_e32 v9, 0
	v_lshl_add_u64 v[4:5], v[4:5], 0, v[8:9]
	v_lshl_add_u64 v[4:5], s[22:23], 0, v[4:5]
	s_mov_b64 s[6:7], 0x6100000
	v_add_u32_e32 v6, 0x9000, v159
	v_add_u32_e32 v7, 0xfffffe00, v158
	v_lshl_add_u64 v[4:5], v[4:5], 0, s[6:7]
	s_mov_b64 s[6:7], 0
	s_mov_b64 s[8:9], 0x60000
	s_movk_i32 s10, 0x6ff
	global_load_dword v8, v[2:3], off
	s_waitcnt vmcnt(0)
.LBB0_138:
	ds_read_b32 v9, v6
	v_add_u32_e32 v7, 0x200, v7
	v_cmp_lt_u32_e32 vcc, s10, v7
	v_add_u32_e32 v6, 0x800, v6
	s_or_b64 s[6:7], vcc, s[6:7]
	s_waitcnt lgkmcnt(0)
	v_add_f32_e32 v10, v9, v8
	global_store_dword v[4:5], v10, off
	v_lshl_add_u64 v[4:5], v[4:5], 0, s[8:9]
	s_andn2_b64 exec, exec, s[6:7]
	s_cbranch_execnz .LBB0_138
	s_or_b64 exec, exec, s[6:7]
	s_barrier
